# v69 + 64-byte alignment of the attention loop's skip-rescale branch targets and the pmat unit loop head
# baseline (speedup 1.0000x reference)
; #define SBAR() __builtin_amdgcn_sched_barrier(0)
; template <int M> __device__ __forceinline__ void fin_slice(f32x16& p0, f32x16& p1, float mreg, float alpha, float& l_reg, FinSt& st, bf16x8 (&pa)[4]) {
;     if constexpr (M < 16) {
;         p1[M] = __builtin_amdgcn_exp2f(p1[M] - mreg);
;         if constexpr (M == 0) st.s0 = p0[0]; else st.s0 += p0[M];
;         if constexpr ((M & 1) == 0) st.c[M / 2] = cvt_pk_n(p0[M], p0[M + 1]);
;     } else if constexpr (M < 20) {
;         constexpr int k = M - 16;
;         if constexpr (k == 0) st.s1 = p1[0]; else st.s1 += p1[4 * k];
;         st.s1 += p1[4 * k + 1]; st.s1 += p1[4 * k + 2]; st.s1 += p1[4 * k + 3];
; template <bool FIN, bool PRE, int DM, class Dma> __device__ __forceinline__ void region_qk(f32x16& ps0, f32x16& ps1, const char* Ks, const bf16x8* qr, const char* qslot, const int (&kb)[4], ...
;     bf16x8 kf[2][2], qf[2]; FinSt st;
;     ...
;     QKT_RD(0, 0);
;     sfor<0, 12>([&](auto d_) { constexpr int d0 = decltype(d_)::value, cb = d0 & 1, nb = cb ^ 1;
;         if constexpr (d0 < 11) QKT_RD(d0 + 1, nb);
;         if constexpr (d0 == 0) ps0 = __builtin_amdgcn_mfma_f32_32x32x16_bf16(kf[cb][0], qf[cb], f32x16{}, 0, 0, 0);
;         else ps0 = __builtin_amdgcn_mfma_f32_32x32x16_bf16(kf[cb][0], qf[cb], ps0, 0, 0, 0);
;         if constexpr (FIN) fin_slice<2 * d0>(pf0, pf1, mreg, alpha, l_reg, st, pa);
;         if constexpr (PRE && d0 >= 10) { constexpr int k = 2 * (d0 - 10); l[k] = tr_read<v_rd_off(0, k, 0)>(vb); h[k] = tr_read<v_rd_off(0, k, 1)>(vb); }
;         __builtin_amdgcn_sched_group_barrier(0x100, 3, 0); __builtin_amdgcn_sched_group_barrier(0x8, 1, 0);
;         SBAR();
;         if constexpr (d0 == 0) ps1 = __builtin_amdgcn_mfma_f32_32x32x16_bf16(kf[cb][1], qf[cb], f32x16{}, 0, 0, 0);
;         else ps1 = __builtin_amdgcn_mfma_f32_32x32x16_bf16(kf[cb][1], qf[cb], ps1, 0, 0, 0);
;         if constexpr (FIN) fin_slice<2 * d0 + 1>(pf0, pf1, mreg, alpha, l_reg, st, pa);
;         if constexpr (PRE && d0 >= 10) { constexpr int k = 2 * (d0 - 10) + 1; l[k] = tr_read<v_rd_off(0, k, 0)>(vb); h[k] = tr_read<v_rd_off(0, k, 1)>(vb); }
;         if constexpr ((d0 & 1) == 0 && d0 < 10 && (DM == 1 || (DM == 2 && d0 >= 6))) dma(std::integral_constant<int, d0 / 2>{});
;         __builtin_amdgcn_sched_group_barrier(0x8, 1, 0);
;         SBAR();
;     });
.LBB0_622:
	ds_read_b128 v[80:83], v242 offset:57344
	ds_read_b128 v[84:87], v243 offset:12288
	ds_read_b128 v[126:129], v244 offset:57344
	ds_read_b128 v[132:135], v245 offset:12288
	v_sub_f32_e32 v64, v64, v130
	v_exp_f32_e32 v131, v64
	v_cvt_pk_bf16_f32 v64, v94, v95
	s_waitcnt lgkmcnt(3)
	v_mfma_f32_32x32x16_bf16 v[110:125], v[80:83], v[186:189], 0
	v_lshlrev_b64 v[80:81], v210, s[46:47]
	v_sub_f32_e32 v65, v65, v130
	v_lshl_add_u64 v[80:81], v[80:81], 1, v[228:229]
	v_exp_f32_e32 v140, v65
	v_add_f32_e32 v65, v94, v95
	s_mov_b32 s12, m0
	s_mov_b32 m0, s65
	s_nop 0
	global_load_lds_dwordx4 v[80:81], off
	s_mov_b32 m0, s12
	s_waitcnt lgkmcnt(2)
	v_mfma_f32_32x32x16_bf16 v[80:95], v[84:87], v[186:189], 0
	ds_read_b128 v[136:139], v246 offset:57344
	ds_read_b128 v[194:197], v247 offset:12288
	s_waitcnt lgkmcnt(3)
	v_mfma_f32_32x32x16_bf16 v[110:125], v[126:129], v[182:185], v[110:125]
	v_sub_f32_e32 v66, v66, v130
	v_exp_f32_e32 v141, v66
	v_add_f32_e32 v66, v96, v65
	v_cvt_pk_bf16_f32 v65, v96, v97
	s_waitcnt lgkmcnt(2)
	v_mfma_f32_32x32x16_bf16 v[80:95], v[132:135], v[182:185], v[80:95]
	v_sub_f32_e32 v67, v67, v130
	v_exp_f32_e32 v223, v67
	v_add_f32_e32 v66, v97, v66
	ds_read_b128 v[126:129], v248 offset:57344
	ds_read_b128 v[132:135], v249 offset:12288
	s_waitcnt lgkmcnt(3)
	v_mfma_f32_32x32x16_bf16 v[110:125], v[136:139], v[178:181], v[110:125]
	v_sub_f32_e32 v67, v68, v130
	v_exp_f32_e32 v225, v67
	v_add_f32_e32 v67, v98, v66
	v_cvt_pk_bf16_f32 v66, v98, v99
	s_waitcnt lgkmcnt(2)
	v_mfma_f32_32x32x16_bf16 v[80:95], v[194:197], v[178:181], v[80:95]
	v_sub_f32_e32 v68, v69, v130
	v_exp_f32_e32 v194, v68
	v_lshlrev_b64 v[68:69], v212, s[46:47]
	v_lshl_add_u64 v[68:69], v[68:69], 1, v[230:231]
	s_mov_b32 s12, m0
	s_mov_b32 m0, s72
	s_nop 0
	global_load_lds_dwordx4 v[68:69], off
	s_mov_b32 m0, s12
	v_add_f32_e32 v67, v99, v67
	ds_read_b128 v[96:99], v242 offset:57472
	ds_read_b128 v[136:139], v243 offset:12416
	s_waitcnt lgkmcnt(3)
	v_mfma_f32_32x32x16_bf16 v[110:125], v[126:129], v[174:177], v[110:125]
	v_sub_f32_e32 v68, v70, v130
	v_exp_f32_e32 v195, v68
	v_add_f32_e32 v68, v100, v67
	v_cvt_pk_bf16_f32 v67, v100, v101
	s_waitcnt lgkmcnt(2)
	v_mfma_f32_32x32x16_bf16 v[80:95], v[132:135], v[174:177], v[80:95]
	v_sub_f32_e32 v69, v71, v130
	v_add_f32_e32 v68, v101, v68
	v_exp_f32_e32 v196, v69
	ds_read_b128 v[126:129], v244 offset:57472
	ds_read_b128 v[132:135], v245 offset:12416
	s_waitcnt lgkmcnt(3)
	v_mfma_f32_32x32x16_bf16 v[110:125], v[96:99], v[170:173], v[110:125]
	v_sub_f32_e32 v69, v72, v130
	v_exp_f32_e32 v197, v69
	v_add_f32_e32 v69, v102, v68
	v_cvt_pk_bf16_f32 v68, v102, v103
	s_waitcnt lgkmcnt(2)
	v_mfma_f32_32x32x16_bf16 v[80:95], v[136:139], v[170:173], v[80:95]
	v_sub_f32_e32 v70, v73, v130
	v_exp_f32_e32 v136, v70
	v_lshlrev_b64 v[70:71], v214, s[46:47]
	v_lshl_add_u64 v[70:71], v[70:71], 1, v[232:233]
	s_mov_b32 s12, m0
	s_mov_b32 m0, s73
	s_nop 0
	global_load_lds_dwordx4 v[70:71], off
	s_mov_b32 m0, s12
	v_add_f32_e32 v69, v103, v69
	ds_read_b128 v[70:73], v246 offset:57472
	ds_read_b128 v[96:99], v247 offset:12416
	s_waitcnt lgkmcnt(3)
	v_mfma_f32_32x32x16_bf16 v[110:125], v[126:129], v[166:169], v[110:125]
	v_sub_f32_e32 v74, v74, v130
	v_exp_f32_e32 v137, v74
	v_add_f32_e32 v74, v104, v69
	v_cvt_pk_bf16_f32 v69, v104, v105
	s_waitcnt lgkmcnt(2)
	v_mfma_f32_32x32x16_bf16 v[80:95], v[132:135], v[166:169], v[80:95]
	v_sub_f32_e32 v75, v75, v130
	v_add_f32_e32 v74, v105, v74
	v_exp_f32_e32 v132, v75
	ds_read_b128 v[100:103], v248 offset:57472
	ds_read_b128 v[126:129], v249 offset:12416
	s_waitcnt lgkmcnt(3)
	v_mfma_f32_32x32x16_bf16 v[110:125], v[70:73], v[162:165], v[110:125]
	v_sub_f32_e32 v70, v76, v130
	v_exp_f32_e32 v133, v70
	v_add_f32_e32 v71, v106, v74
	v_cvt_pk_bf16_f32 v70, v106, v107
	s_waitcnt lgkmcnt(2)
	v_mfma_f32_32x32x16_bf16 v[80:95], v[96:99], v[162:165], v[80:95]
	s_add_u32 s48, s42, 0xfffc0000
	s_addc_u32 s49, s43, -1
	s_mov_b32 s12, m0
	s_mov_b32 m0, s64
	s_nop 0
	global_load_lds_dwordx4 v211, s[48:49]
	s_mov_b32 m0, s12
	v_sub_f32_e32 v72, v77, v130
	v_add_f32_e32 v71, v107, v71
	v_exp_f32_e32 v134, v72
	ds_read_b128 v[72:75], v242 offset:57600
	ds_read_b128 v[96:99], v243 offset:12544
	s_waitcnt lgkmcnt(3)
	v_mfma_f32_32x32x16_bf16 v[110:125], v[100:103], v[158:161], v[110:125]
	v_sub_f32_e32 v76, v78, v130
	v_exp_f32_e32 v135, v76
	v_add_f32_e32 v76, v108, v71
	v_cvt_pk_bf16_f32 v71, v108, v109
	s_waitcnt lgkmcnt(2)
	v_mfma_f32_32x32x16_bf16 v[80:95], v[126:129], v[158:161], v[80:95]
	v_sub_f32_e32 v77, v79, v130
	v_exp_f32_e32 v108, v77
	v_add_f32_e32 v109, v109, v76
	ds_read_b128 v[76:79], v244 offset:57600
	ds_read_b128 v[100:103], v245 offset:12544
	s_waitcnt lgkmcnt(3)
	v_mfma_f32_32x32x16_bf16 v[110:125], v[72:75], v[154:157], v[110:125]
	v_add_f32_e32 v72, v131, v140
	v_add_f32_e32 v72, v141, v72
	v_add_f32_e32 v74, v223, v72
	v_cvt_pk_bf16_f32 v72, v131, v140
	v_cvt_pk_bf16_f32 v73, v141, v223
	v_permlane32_swap_b32_e32 v64, v66
	v_permlane32_swap_b32_e32 v65, v67
	s_waitcnt lgkmcnt(2)
	v_mfma_f32_32x32x16_bf16 v[80:95], v[96:99], v[154:157], v[80:95]
	v_add_f32_e32 v74, v225, v74
	v_add_f32_e32 v74, v194, v74
	s_mov_b32 s12, m0
	s_mov_b32 m0, s63
	s_nop 0
	global_load_lds_dwordx4 v213, s[48:49]
	s_mov_b32 m0, s12
	v_add_f32_e32 v74, v195, v74
	v_add_f32_e32 v126, v196, v74
	v_cvt_pk_bf16_f32 v74, v225, v194
	v_cvt_pk_bf16_f32 v75, v195, v196
	v_permlane32_swap_b32_e32 v68, v70
	v_permlane32_swap_b32_e32 v69, v71
	ds_read_b128 v[96:99], v246 offset:57600
	ds_read_b128 v[104:107], v247 offset:12544
	s_waitcnt lgkmcnt(3)
; template <int N> __device__ __forceinline__ void psm_slice(f32x16& p0, f32x16& p1, float& m_reg, float& alpha, PsmSt& st) {
;     if constexpr (N == 0) { float c = fmaxf(p0[0], p0[1]);
; #pragma unroll
;         for (int r = 2; r < 16; r += 2) c = fmaxf(fmaxf(c, p0[r]), p0[r + 1]);
;         st.c0 = c; }
;     else if constexpr (N == 1) { float c = fmaxf(p1[0], p1[1]);
; #pragma unroll
;         for (int r = 2; r < 16; r += 2) c = fmaxf(fmaxf(c, p1[r]), p1[r + 1]);
;         st.c1 = c; }
;     else if constexpr (N == 2) { float pmax = fmaxf(st.c0, st.c1);
;         auto rr = __builtin_amdgcn_permlane32_swap(__float_as_uint(pmax), __float_as_uint(pmax), false, false); pmax = fmaxf(__uint_as_float(rr[0]), __uint_as_float(rr[1]));
;         const bool keep = __all(pmax - m_reg <= THR2);
;         st.mn = keep ? m_reg : fmaxf(m_reg, pmax); }
;     else if constexpr (N == 3) { alpha = __builtin_amdgcn_exp2f(m_reg - st.mn); m_reg = st.mn; }
;     else if constexpr (N < 8) { constexpr int r = 2 * (N - 4); p0[r] = __builtin_amdgcn_exp2f(p0[r] - st.mn); p0[r + 1] = __builtin_amdgcn_exp2f(p0[r + 1] - st.mn); }
;     else { constexpr int r = N; p0[r] = __builtin_amdgcn_exp2f(p0[r] - st.mn); }
; }
; template <bool PSM, bool PRE> __device__ __forceinline__ void region_pv(f32x16* o, int vb, const bf16x8 (&pa)[4], f32x16& pn0, f32x16& pn1, float& m_reg, float& alpha, s16x4 (&l)[4], s16x4 (&h)[4]) {
;     PsmSt st;
;     if constexpr (!PRE) {
;     l[0] = tr_read<v_rd_off(0, 0, 0)>(vb); h[0] = tr_read<v_rd_off(0, 0, 1)>(vb); l[1] = tr_read<v_rd_off(0, 1, 0)>(vb); h[1] = tr_read<v_rd_off(0, 1, 1)>(vb);
;     l[2] = tr_read<v_rd_off(0, 2, 0)>(vb); h[2] = tr_read<v_rd_off(0, 2, 1)>(vb); l[3] = tr_read<v_rd_off(0, 3, 0)>(vb); h[3] = tr_read<v_rd_off(0, 3, 1)>(vb);
;     SBAR(); }
;     sfor<0, 16>([&](auto n_) { constexpr int n = decltype(n_)::value, b = n >> 2, k = n & 3;
;         o[b] = __builtin_amdgcn_mfma_f32_32x32x16_bf16(pa[k], (bf16x8){l[k][0], l[k][1], l[k][2], l[k][3], h[k][0], h[k][1], h[k][2], h[k][3]}, o[b], 0, 0, 0);
;         if constexpr (b < 3) { l[k] = tr_read<v_rd_off((b + 1) & 3, k, 0)>(vb); h[k] = tr_read<v_rd_off((b + 1) & 3, k, 1)>(vb); }
;         if constexpr (PSM) psm_slice<n>(pn0, pn1, m_reg, alpha, st);
;         __builtin_amdgcn_sched_group_barrier(0x8, 1, 0); __builtin_amdgcn_sched_group_barrier(0x100, 2, 0);
;         SBAR();
;     });
; }
	v_mfma_f32_32x32x16_bf16 v[110:125], v[76:79], v[150:153], v[110:125]
	v_add_f32_e32 v76, v197, v126
	v_add_f32_e32 v76, v136, v76
	v_add_f32_e32 v76, v137, v76
	v_add_f32_e32 v78, v132, v76
	v_cvt_pk_bf16_f32 v76, v197, v136
	v_cvt_pk_bf16_f32 v77, v137, v132
	s_waitcnt lgkmcnt(2)
	v_mfma_f32_32x32x16_bf16 v[80:95], v[100:103], v[150:153], v[80:95]
	v_add_f32_e32 v78, v133, v78
	v_add_f32_e32 v78, v134, v78
	v_add_f32_e32 v78, v135, v78
	v_add_f32_e32 v131, v108, v78
	v_cvt_pk_bf16_f32 v78, v133, v134
	v_cvt_pk_bf16_f32 v79, v135, v108
	ds_read_b128 v[132:135], v248 offset:57600
	ds_read_b128 v[136:139], v249 offset:12544
	ds_read_b64_tr_b16 v[100:101], v251
	s_waitcnt lgkmcnt(4)
	v_mfma_f32_32x32x16_bf16 v[110:125], v[96:99], v[146:149], v[110:125]
	ds_read_b64_tr_b16 v[102:103], v251 offset:2048
	v_permlane32_swap_b32_e32 v72, v74
	v_permlane32_swap_b32_e32 v73, v75
	s_waitcnt lgkmcnt(4)
	v_mfma_f32_32x32x16_bf16 v[80:95], v[104:107], v[146:149], v[80:95]
	ds_read_b64_tr_b16 v[126:127], v251 offset:4096
	ds_read_b64_tr_b16 v[128:129], v251 offset:6144
	v_permlane32_swap_b32_e32 v76, v78
	v_permlane32_swap_b32_e32 v77, v79
	ds_read_b64_tr_b16 v[104:105], v251 offset:8192
	ds_read_b64_tr_b16 v[106:107], v251 offset:10240
	s_waitcnt lgkmcnt(7)
	v_mfma_f32_32x32x16_bf16 v[110:125], v[132:135], v[142:145], v[110:125]
	v_add_f32_e32 v223, v109, v131
	v_mov_b32_e32 v225, v223
	s_nop 1
	v_permlane32_swap_b32_e32 v223, v225
	s_waitcnt lgkmcnt(6)
	v_mfma_f32_32x32x16_bf16 v[80:95], v[136:139], v[142:145], v[80:95]
	ds_read_b64_tr_b16 v[96:97], v251 offset:12288
	ds_read_b64_tr_b16 v[98:99], v251 offset:14336
	s_cmp_lg_u32 s46, 2
	s_cbranch_scc1 .LBB0_624
	s_nop 7
	v_mov_b32_e32 v80, 0xff800000
	v_mov_b32_e32 v81, v80
	v_mov_b32_e32 v82, v80
	v_mov_b32_e32 v83, v80
	v_mov_b32_e32 v84, v80
	v_mov_b32_e32 v85, v80
	v_mov_b32_e32 v86, v80
	v_mov_b32_e32 v87, v80
	v_mov_b32_e32 v110, v80
	v_mov_b32_e32 v111, v80
	v_mov_b32_e32 v112, v80
	v_mov_b32_e32 v113, v80
	v_mov_b32_e32 v114, v80
	v_mov_b32_e32 v115, v80
	v_mov_b32_e32 v116, v80
	v_mov_b32_e32 v117, v80
	v_mov_b32_e32 v118, v80
	v_mov_b32_e32 v119, v80
	v_mov_b32_e32 v120, v80
	v_mov_b32_e32 v121, v80
	v_mov_b32_e32 v122, v80
	v_mov_b32_e32 v123, v80
	v_mov_b32_e32 v124, v80
	v_mov_b32_e32 v125, v80
	.p2align 6
.LBB0_624:
	s_waitcnt lgkmcnt(6)
	v_mfma_f32_32x32x16_bf16 v[0:15], v[64:67], v[100:103], v[0:15]
	v_max3_f32 v108, v110, v111, v112
	v_max3_f32 v108, v108, v113, v114
	ds_read_b64_tr_b16 v[100:101], v251 offset:512
	ds_read_b64_tr_b16 v[102:103], v251 offset:2560
	v_max3_f32 v108, v108, v115, v116
	v_max3_f32 v108, v108, v117, v118
	v_max3_f32 v108, v108, v119, v120
	v_max3_f32 v108, v108, v121, v122
	v_max3_f32 v108, v108, v123, v124
	s_waitcnt lgkmcnt(6)
	v_mfma_f32_32x32x16_bf16 v[0:15], v[68:71], v[126:129], v[0:15]
	v_max_f32_e32 v109, v81, v81
	v_max_f32_e32 v126, v80, v80
	v_max_f32_e32 v109, v126, v109
	v_max3_f32 v109, v109, v82, v83
	ds_read_b64_tr_b16 v[132:133], v251 offset:4608
	ds_read_b64_tr_b16 v[134:135], v251 offset:6656
	v_max3_f32 v109, v109, v84, v85
	v_max3_f32 v109, v109, v86, v87
	v_max3_f32 v109, v109, v88, v89
	v_max3_f32 v109, v109, v90, v91
	v_max3_f32 v109, v109, v92, v93
	v_max3_f32 v109, v109, v94, v95
	v_max3_f32 v108, v108, v125, v109
	v_mov_b32_e32 v109, v108
	s_waitcnt lgkmcnt(6)
	v_mfma_f32_32x32x16_bf16 v[0:15], v[72:75], v[104:107], v[0:15]
	v_permlane32_swap_b32_e32 v108, v109
	v_max_f32_e32 v109, v109, v109
	v_max_f32_e32 v108, v108, v108
	v_max_f32_e32 v108, v108, v109
	v_sub_f32_e32 v109, v108, v130
	ds_read_b64_tr_b16 v[104:105], v251 offset:8704
	ds_read_b64_tr_b16 v[106:107], v251 offset:10752
	v_cmp_ge_f32_e32 vcc, s33, v109
	s_cmp_eq_u64 vcc, exec
	v_max_f32_e32 v109, v130, v130
	s_cselect_b64 vcc, -1, 0
	v_max_f32_e32 v108, v109, v108
	v_cndmask_b32_e32 v252, v108, v130, vcc
	s_waitcnt lgkmcnt(6)
	v_mfma_f32_32x32x16_bf16 v[0:15], v[76:79], v[96:99], v[0:15]
	v_sub_f32_e32 v108, v130, v252
	ds_read_b64_tr_b16 v[96:97], v251 offset:12800
	ds_read_b64_tr_b16 v[98:99], v251 offset:14848
	v_exp_f32_e32 v227, v108
	s_waitcnt lgkmcnt(6)
	v_mfma_f32_32x32x16_bf16 v[48:63], v[64:67], v[100:103], v[48:63]
	v_sub_f32_e32 v108, v110, v252
	v_exp_f32_e32 v126, v108
	v_sub_f32_e32 v108, v111, v252
	ds_read_b64_tr_b16 v[100:101], v251 offset:1024
	ds_read_b64_tr_b16 v[102:103], v251 offset:3072
	v_exp_f32_e32 v127, v108
	s_waitcnt lgkmcnt(6)
	v_mfma_f32_32x32x16_bf16 v[48:63], v[68:71], v[132:135], v[48:63]
	v_sub_f32_e32 v112, v112, v252
	v_exp_f32_e32 v128, v112
	v_sub_f32_e32 v112, v113, v252
	ds_read_b64_tr_b16 v[108:109], v251 offset:5120
	ds_read_b64_tr_b16 v[110:111], v251 offset:7168
	v_exp_f32_e32 v129, v112
	s_waitcnt lgkmcnt(6)
	v_mfma_f32_32x32x16_bf16 v[48:63], v[72:75], v[104:107], v[48:63]
	v_sub_f32_e32 v112, v114, v252
	v_exp_f32_e32 v130, v112
	v_sub_f32_e32 v112, v115, v252
	ds_read_b64_tr_b16 v[104:105], v251 offset:9216
	ds_read_b64_tr_b16 v[106:107], v251 offset:11264
	v_exp_f32_e32 v131, v112
	s_waitcnt lgkmcnt(6)
	v_mfma_f32_32x32x16_bf16 v[48:63], v[76:79], v[96:99], v[48:63]
	v_sub_f32_e32 v112, v116, v252
	v_exp_f32_e32 v132, v112
	v_sub_f32_e32 v112, v117, v252
	ds_read_b64_tr_b16 v[96:97], v251 offset:13312
	ds_read_b64_tr_b16 v[98:99], v251 offset:15360
	v_exp_f32_e32 v133, v112
	s_waitcnt lgkmcnt(6)
	v_mfma_f32_32x32x16_bf16 v[32:47], v[64:67], v[100:103], v[32:47]
	v_sub_f32_e32 v112, v118, v252
	ds_read_b64_tr_b16 v[100:101], v251 offset:1536
	ds_read_b64_tr_b16 v[102:103], v251 offset:3584
	v_exp_f32_e32 v134, v112
	s_waitcnt lgkmcnt(6)
	v_mfma_f32_32x32x16_bf16 v[32:47], v[68:71], v[108:111], v[32:47]
	v_sub_f32_e32 v112, v119, v252
	ds_read_b64_tr_b16 v[108:109], v251 offset:5632
	ds_read_b64_tr_b16 v[110:111], v251 offset:7680
	v_exp_f32_e32 v135, v112
	s_waitcnt lgkmcnt(6)
	v_mfma_f32_32x32x16_bf16 v[32:47], v[72:75], v[104:107], v[32:47]
	v_sub_f32_e32 v112, v120, v252
	ds_read_b64_tr_b16 v[104:105], v251 offset:9728
	ds_read_b64_tr_b16 v[106:107], v251 offset:11776
	v_exp_f32_e32 v136, v112
	s_waitcnt lgkmcnt(6)
	v_mfma_f32_32x32x16_bf16 v[32:47], v[76:79], v[96:99], v[32:47]
	v_sub_f32_e32 v112, v121, v252
	ds_read_b64_tr_b16 v[96:97], v251 offset:13824
	ds_read_b64_tr_b16 v[98:99], v251 offset:15872
	v_exp_f32_e32 v137, v112
	s_waitcnt lgkmcnt(6)
	v_mfma_f32_32x32x16_bf16 v[16:31], v[64:67], v[100:103], v[16:31]
	v_sub_f32_e32 v64, v122, v252
	v_exp_f32_e32 v138, v64
	s_waitcnt lgkmcnt(4)
	v_mfma_f32_32x32x16_bf16 v[16:31], v[68:71], v[108:111], v[16:31]
	v_sub_f32_e32 v64, v123, v252
	v_exp_f32_e32 v139, v64
	s_waitcnt lgkmcnt(2)
	v_mfma_f32_32x32x16_bf16 v[16:31], v[72:75], v[104:107], v[16:31]
	v_sub_f32_e32 v64, v124, v252
	v_exp_f32_e32 v140, v64
	s_waitcnt lgkmcnt(0)
	v_mfma_f32_32x32x16_bf16 v[16:31], v[76:79], v[96:99], v[16:31]
	v_sub_f32_e32 v64, v125, v252
	v_exp_f32_e32 v141, v64
	v_cmp_gt_f32_e32 vcc, 1.0, v227
	s_cbranch_vccz .LBB0_628
; #define SBAR() __builtin_amdgcn_sched_barrier(0)
; #define PIN2(A, B) asm volatile("" : "+v"(A), "+v"(B))
; #define WAITV(N) asm volatile("s_waitcnt vmcnt(" #N ")" ::: "memory")
; #define LBAR() asm volatile("s_waitcnt lgkmcnt(0)\n\ts_barrier" ::: "memory")
; #define RESC(a) do { if (__any((a) < 1.f)) { if (hi == 0) al_l[r32] = (a); asm volatile("s_waitcnt lgkmcnt(0)" ::: "memory"); \
;     _Pragma("unroll") for (int d = 0; d < 4; ++d) _Pragma("unroll") for (int r = 0; r < 16; ++r) o[d][r] *= al_l[crow(r, hi)]; } } while (0)
; #define DMA_FN(KT, KB, VT, VBUF) [&](auto pc_) { constexpr int pc = decltype(pc_)::value; \
;         if constexpr (pc < 3) glds16(ksrc[pc] + (size_t)(KT) * (krope[pc] ? KVBLK * 64 : KVBLK * 2048), lK + (KB) * SHM_K + pc * 1024); \
;         else rscan::glds16u(Vs + (size_t)(VT) * KVBLK * 2048, vsrc[pc - 3], lV + (VBUF) * SHM_V + (pc - 3) * 1024); }
; __device__ __forceinline__ void attn_unit(const bf16_t* __restrict__ Qs, const bf16_t* __restrict__ Kn, const bf16_t* __restrict__ Kr, const bf16_t* __restrict__ Vs, bf16_t* Os, int q0, int Lp, char* lds, const int tid) {
;     ...
;         region_pv<true, true>(o, vb0, pa, pB0, pB1, m_reg, alB, vl, vh); PIN2(pB0, pB1);
;         RESC(alB);
;         WAITV(0); LBAR();
;         SBAR(); region_qk<true, true, 1>(pA0, pA1, K_lds, qr, qslot, kb, pB0, pB1, m_reg, alB, l_reg, pa, vb0 + SHM_V, vl, vh, DMA_FN(j + 2, 1, j + 1, 0));
;         region_pv<true, true>(o, vb0 + SHM_V, pa, pA0, pA1, m_reg, alA, vl, vh); PIN2(pA0, pA1);
	s_and_saveexec_b64 s[48:49], s[40:41]
	ds_write_b32 v215, v227 offset:128
	s_or_b64 exec, exec, s[48:49]
	s_waitcnt lgkmcnt(0)
	ds_read_b128 v[64:67], v250 offset:224
	ds_read_b128 v[68:71], v250 offset:192
	ds_read_b128 v[72:75], v250 offset:160
	ds_read_b128 v[76:79], v250 offset:128
	s_waitcnt lgkmcnt(3)
	v_pk_mul_f32 v[14:15], v[14:15], v[66:67]
	s_waitcnt lgkmcnt(2)
	v_pk_mul_f32 v[10:11], v[10:11], v[70:71]
	s_waitcnt lgkmcnt(1)
	v_pk_mul_f32 v[6:7], v[6:7], v[74:75]
	s_waitcnt lgkmcnt(0)
	v_pk_mul_f32 v[2:3], v[2:3], v[78:79]
	v_pk_mul_f32 v[12:13], v[12:13], v[64:65]
	v_pk_mul_f32 v[8:9], v[8:9], v[68:69]
	v_pk_mul_f32 v[4:5], v[4:5], v[72:73]
	v_pk_mul_f32 v[0:1], v[0:1], v[76:77]
	v_pk_mul_f32 v[62:63], v[62:63], v[66:67]
	v_pk_mul_f32 v[58:59], v[58:59], v[70:71]
	v_pk_mul_f32 v[54:55], v[54:55], v[74:75]
	v_pk_mul_f32 v[50:51], v[50:51], v[78:79]
	v_pk_mul_f32 v[60:61], v[60:61], v[64:65]
	v_pk_mul_f32 v[56:57], v[56:57], v[68:69]
	v_pk_mul_f32 v[52:53], v[52:53], v[72:73]
	v_pk_mul_f32 v[48:49], v[48:49], v[76:77]
	v_pk_mul_f32 v[46:47], v[46:47], v[66:67]
	v_pk_mul_f32 v[42:43], v[42:43], v[70:71]
	v_pk_mul_f32 v[38:39], v[38:39], v[74:75]
	v_pk_mul_f32 v[34:35], v[34:35], v[78:79]
	v_pk_mul_f32 v[44:45], v[44:45], v[64:65]
	v_pk_mul_f32 v[40:41], v[40:41], v[68:69]
	v_pk_mul_f32 v[36:37], v[36:37], v[72:73]
	v_pk_mul_f32 v[32:33], v[32:33], v[76:77]
	v_pk_mul_f32 v[30:31], v[30:31], v[66:67]
	v_pk_mul_f32 v[26:27], v[26:27], v[70:71]
	v_pk_mul_f32 v[22:23], v[22:23], v[74:75]
	v_pk_mul_f32 v[18:19], v[18:19], v[78:79]
	v_pk_mul_f32 v[28:29], v[28:29], v[64:65]
	v_pk_mul_f32 v[24:25], v[24:25], v[68:69]
	v_pk_mul_f32 v[20:21], v[20:21], v[72:73]
	v_pk_mul_f32 v[16:17], v[16:17], v[76:77]
	.p2align 6
.LBB0_628:
	s_waitcnt vmcnt(0)
	s_waitcnt lgkmcnt(0)
	s_barrier
	ds_read_b128 v[64:67], v242 offset:32768
	ds_read_b128 v[68:71], v242 offset:45056
	ds_read_b128 v[112:115], v244 offset:32768
	ds_read_b128 v[116:119], v244 offset:45056
	v_sub_f32_e32 v72, v80, v252
	v_exp_f32_e32 v194, v72
	v_cvt_pk_bf16_f32 v80, v126, v127
	s_waitcnt lgkmcnt(3)
	v_mfma_f32_32x32x16_bf16 v[96:111], v[64:67], v[186:189], 0
	s_waitcnt lgkmcnt(2)
	v_mfma_f32_32x32x16_bf16 v[64:79], v[68:71], v[186:189], 0
	s_add_u32 s48, s46, 1
	s_addc_u32 s49, s47, 0
	v_lshlrev_b64 v[120:121], v210, s[48:49]
	v_lshl_add_u64 v[120:121], v[120:121], 1, v[228:229]
	s_mov_b32 s12, m0
	s_mov_b32 m0, s66
	s_nop 0
	global_load_lds_dwordx4 v[120:121], off
	s_mov_b32 m0, s12
	v_sub_f32_e32 v81, v81, v252
	v_exp_f32_e32 v195, v81
	v_add_f32_e32 v81, v126, v127
	ds_read_b128 v[120:123], v246 offset:32768
	ds_read_b128 v[124:127], v246 offset:45056
	s_waitcnt lgkmcnt(3)
	v_mfma_f32_32x32x16_bf16 v[96:111], v[112:115], v[182:185], v[96:111]
	v_sub_f32_e32 v82, v82, v252
	v_exp_f32_e32 v196, v82
	v_add_f32_e32 v82, v128, v81
	v_cvt_pk_bf16_f32 v81, v128, v129
	s_waitcnt lgkmcnt(2)
	v_mfma_f32_32x32x16_bf16 v[64:79], v[116:119], v[182:185], v[64:79]
	v_sub_f32_e32 v83, v83, v252
	v_exp_f32_e32 v128, v83
	v_add_f32_e32 v82, v129, v82
	ds_read_b128 v[112:115], v248 offset:32768
	ds_read_b128 v[116:119], v248 offset:45056
	s_waitcnt lgkmcnt(3)
	v_mfma_f32_32x32x16_bf16 v[96:111], v[120:123], v[178:181], v[96:111]
	v_sub_f32_e32 v83, v84, v252
	v_exp_f32_e32 v129, v83
	v_add_f32_e32 v83, v130, v82
	v_cvt_pk_bf16_f32 v82, v130, v131
	s_waitcnt lgkmcnt(2)
	v_mfma_f32_32x32x16_bf16 v[64:79], v[124:127], v[178:181], v[64:79]
	v_sub_f32_e32 v84, v85, v252
	v_exp_f32_e32 v130, v84
	v_lshlrev_b64 v[84:85], v212, s[48:49]
	v_lshl_add_u64 v[84:85], v[84:85], 1, v[230:231]
	s_mov_b32 s12, m0
	s_mov_b32 m0, s67
	s_nop 0
	global_load_lds_dwordx4 v[84:85], off
	s_mov_b32 m0, s12
	v_add_f32_e32 v83, v131, v83
	ds_read_b128 v[120:123], v242 offset:32896
	ds_read_b128 v[124:127], v242 offset:45184
	s_waitcnt lgkmcnt(3)
	v_mfma_f32_32x32x16_bf16 v[96:111], v[112:115], v[174:177], v[96:111]
	v_sub_f32_e32 v84, v86, v252
	v_exp_f32_e32 v131, v84
	v_add_f32_e32 v84, v132, v83
	v_cvt_pk_bf16_f32 v83, v132, v133
	s_waitcnt lgkmcnt(2)
	v_mfma_f32_32x32x16_bf16 v[64:79], v[116:119], v[174:177], v[64:79]
	v_sub_f32_e32 v85, v87, v252
	v_exp_f32_e32 v132, v85
	v_add_f32_e32 v84, v133, v84
	ds_read_b128 v[112:115], v244 offset:32896
	ds_read_b128 v[116:119], v244 offset:45184
	s_waitcnt lgkmcnt(3)
	v_mfma_f32_32x32x16_bf16 v[96:111], v[120:123], v[170:173], v[96:111]
	v_sub_f32_e32 v85, v88, v252
	v_exp_f32_e32 v133, v85
	v_add_f32_e32 v85, v134, v84
	v_cvt_pk_bf16_f32 v84, v134, v135
	s_waitcnt lgkmcnt(2)
	v_mfma_f32_32x32x16_bf16 v[64:79], v[124:127], v[170:173], v[64:79]
	v_sub_f32_e32 v86, v89, v252
	v_exp_f32_e32 v126, v86
	v_lshlrev_b64 v[86:87], v214, s[48:49]
	v_lshl_add_u64 v[86:87], v[86:87], 1, v[232:233]
	s_mov_b32 s12, m0
	s_mov_b32 m0, s68
	s_nop 0
	global_load_lds_dwordx4 v[86:87], off
	s_mov_b32 m0, s12
	v_add_f32_e32 v85, v135, v85
	ds_read_b128 v[86:89], v246 offset:32896
	ds_read_b128 v[120:123], v246 offset:45184
	s_waitcnt lgkmcnt(3)
	v_mfma_f32_32x32x16_bf16 v[96:111], v[112:115], v[166:169], v[96:111]
	v_sub_f32_e32 v90, v90, v252
	v_exp_f32_e32 v127, v90
	v_add_f32_e32 v90, v136, v85
	v_cvt_pk_bf16_f32 v85, v136, v137
	s_waitcnt lgkmcnt(2)
	v_mfma_f32_32x32x16_bf16 v[64:79], v[116:119], v[166:169], v[64:79]
	v_sub_f32_e32 v91, v91, v252
	v_exp_f32_e32 v134, v91
	v_add_f32_e32 v90, v137, v90
	ds_read_b128 v[112:115], v248 offset:32896
	ds_read_b128 v[116:119], v248 offset:45184
	s_waitcnt lgkmcnt(3)
	v_mfma_f32_32x32x16_bf16 v[96:111], v[86:89], v[162:165], v[96:111]
	v_sub_f32_e32 v86, v92, v252
	v_exp_f32_e32 v135, v86
	v_add_f32_e32 v87, v138, v90
	v_cvt_pk_bf16_f32 v86, v138, v139
	s_waitcnt lgkmcnt(2)
; template <bool FIN, bool PRE, int DM, class Dma> __device__ __forceinline__ void region_qk(f32x16& ps0, f32x16& ps1, const char* Ks, const bf16x8* qr, const char* qslot, const int (&kb)[4], ...
;     bf16x8 kf[2][2], qf[2]; FinSt st;
;     ...
;     QKT_RD(0, 0);
;     sfor<0, 12>([&](auto d_) { constexpr int d0 = decltype(d_)::value, cb = d0 & 1, nb = cb ^ 1;
;         if constexpr (d0 < 11) QKT_RD(d0 + 1, nb);
;         if constexpr (d0 == 0) ps0 = __builtin_amdgcn_mfma_f32_32x32x16_bf16(kf[cb][0], qf[cb], f32x16{}, 0, 0, 0);
;         else ps0 = __builtin_amdgcn_mfma_f32_32x32x16_bf16(kf[cb][0], qf[cb], ps0, 0, 0, 0);
;         if constexpr (FIN) fin_slice<2 * d0>(pf0, pf1, mreg, alpha, l_reg, st, pa);
;         if constexpr (PRE && d0 >= 10) { constexpr int k = 2 * (d0 - 10); l[k] = tr_read<v_rd_off(0, k, 0)>(vb); h[k] = tr_read<v_rd_off(0, k, 1)>(vb); }
;         __builtin_amdgcn_sched_group_barrier(0x100, 3, 0); __builtin_amdgcn_sched_group_barrier(0x8, 1, 0);
;         SBAR();
;         if constexpr (d0 == 0) ps1 = __builtin_amdgcn_mfma_f32_32x32x16_bf16(kf[cb][1], qf[cb], f32x16{}, 0, 0, 0);
;         else ps1 = __builtin_amdgcn_mfma_f32_32x32x16_bf16(kf[cb][1], qf[cb], ps1, 0, 0, 0);
;         if constexpr (FIN) fin_slice<2 * d0 + 1>(pf0, pf1, mreg, alpha, l_reg, st, pa);
;         if constexpr (PRE && d0 >= 10) { constexpr int k = 2 * (d0 - 10) + 1; l[k] = tr_read<v_rd_off(0, k, 0)>(vb); h[k] = tr_read<v_rd_off(0, k, 1)>(vb); }
;         if constexpr ((d0 & 1) == 0 && d0 < 10 && (DM == 1 || (DM == 2 && d0 >= 6))) dma(std::integral_constant<int, d0 / 2>{});
;         __builtin_amdgcn_sched_group_barrier(0x8, 1, 0);
;         SBAR();
;     });
; template <bool PSM, bool PRE> __device__ __forceinline__ void region_pv(f32x16* o, int vb, const bf16x8 (&pa)[4], f32x16& pn0, f32x16& pn1, float& m_reg, float& alpha, s16x4 (&l)[4], s16x4 (&h)[4]) {
;     PsmSt st;
;     if constexpr (!PRE) {
;     l[0] = tr_read<v_rd_off(0, 0, 0)>(vb); h[0] = tr_read<v_rd_off(0, 0, 1)>(vb); l[1] = tr_read<v_rd_off(0, 1, 0)>(vb); h[1] = tr_read<v_rd_off(0, 1, 1)>(vb);
;     l[2] = tr_read<v_rd_off(0, 2, 0)>(vb); h[2] = tr_read<v_rd_off(0, 2, 1)>(vb); l[3] = tr_read<v_rd_off(0, 3, 0)>(vb); h[3] = tr_read<v_rd_off(0, 3, 1)>(vb);
;     SBAR(); }
;     sfor<0, 16>([&](auto n_) { constexpr int n = decltype(n_)::value, b = n >> 2, k = n & 3;
	v_mfma_f32_32x32x16_bf16 v[64:79], v[120:123], v[162:165], v[64:79]
	s_mov_b32 s12, m0
	s_mov_b32 m0, s69
	s_nop 0
	global_load_lds_dwordx4 v211, s[42:43]
	s_mov_b32 m0, s12
	v_sub_f32_e32 v88, v93, v252
	v_exp_f32_e32 v136, v88
	v_add_f32_e32 v87, v139, v87
	ds_read_b128 v[88:91], v242 offset:33024
	ds_read_b128 v[120:123], v242 offset:45312
	s_waitcnt lgkmcnt(3)
	v_mfma_f32_32x32x16_bf16 v[96:111], v[112:115], v[158:161], v[96:111]
	v_sub_f32_e32 v92, v94, v252
	v_exp_f32_e32 v137, v92
	v_add_f32_e32 v92, v140, v87
	v_cvt_pk_bf16_f32 v87, v140, v141
	s_waitcnt lgkmcnt(2)
	v_mfma_f32_32x32x16_bf16 v[64:79], v[116:119], v[158:161], v[64:79]
	v_sub_f32_e32 v93, v95, v252
	v_exp_f32_e32 v138, v93
	v_add_f32_e32 v139, v141, v92
	ds_read_b128 v[92:95], v244 offset:33024
	ds_read_b128 v[114:117], v244 offset:45312
	s_waitcnt lgkmcnt(3)
	v_mfma_f32_32x32x16_bf16 v[96:111], v[88:91], v[154:157], v[96:111]
	v_add_f32_e32 v88, v194, v195
	v_add_f32_e32 v88, v196, v88
	v_add_f32_e32 v90, v128, v88
	v_cvt_pk_bf16_f32 v88, v194, v195
	v_cvt_pk_bf16_f32 v89, v196, v128
	v_permlane32_swap_b32_e32 v80, v82
	v_permlane32_swap_b32_e32 v81, v83
	s_waitcnt lgkmcnt(2)
	v_mfma_f32_32x32x16_bf16 v[64:79], v[120:123], v[154:157], v[64:79]
	v_add_f32_e32 v90, v129, v90
	s_mov_b32 s12, m0
	s_mov_b32 m0, s70
	s_nop 0
	global_load_lds_dwordx4 v213, s[42:43]
	s_mov_b32 m0, s12
	v_add_f32_e32 v90, v130, v90
	v_add_f32_e32 v90, v131, v90
	v_add_f32_e32 v112, v132, v90
	v_cvt_pk_bf16_f32 v90, v129, v130
	v_cvt_pk_bf16_f32 v91, v131, v132
	v_permlane32_swap_b32_e32 v84, v86
	v_permlane32_swap_b32_e32 v85, v87
	ds_read_b128 v[118:121], v246 offset:33024
	ds_read_b128 v[122:125], v246 offset:45312
	s_waitcnt lgkmcnt(3)
	v_mfma_f32_32x32x16_bf16 v[96:111], v[92:95], v[150:153], v[96:111]
	v_add_f32_e32 v92, v133, v112
	v_add_f32_e32 v92, v126, v92
	v_add_f32_e32 v92, v127, v92
	v_add_f32_e32 v92, v134, v92
	v_cvt_pk_bf16_f32 v112, v133, v126
	v_cvt_pk_bf16_f32 v113, v127, v134
	s_waitcnt lgkmcnt(2)
	v_mfma_f32_32x32x16_bf16 v[64:79], v[114:117], v[150:153], v[64:79]
	v_add_f32_e32 v92, v135, v92
	v_add_f32_e32 v92, v136, v92
	v_add_f32_e32 v92, v137, v92
	v_add_f32_e32 v130, v138, v92
	v_cvt_pk_bf16_f32 v114, v135, v136
	v_cvt_pk_bf16_f32 v115, v137, v138
	ds_read_b128 v[92:95], v248 offset:33024
	ds_read_b128 v[126:129], v248 offset:45312
	ds_read_b64_tr_b16 v[116:117], v251 offset:16384
	s_waitcnt lgkmcnt(4)
	v_mfma_f32_32x32x16_bf16 v[96:111], v[118:121], v[146:149], v[96:111]
	ds_read_b64_tr_b16 v[118:119], v251 offset:18432
	v_permlane32_swap_b32_e32 v88, v90
	v_permlane32_swap_b32_e32 v89, v91
	s_waitcnt lgkmcnt(4)
	v_mfma_f32_32x32x16_bf16 v[64:79], v[122:125], v[146:149], v[64:79]
	ds_read_b64_tr_b16 v[120:121], v251 offset:20480
	ds_read_b64_tr_b16 v[122:123], v251 offset:22528
	v_permlane32_swap_b32_e32 v112, v114
	v_permlane32_swap_b32_e32 v113, v115
	ds_read_b64_tr_b16 v[132:133], v251 offset:26624
	s_waitcnt lgkmcnt(6)
	v_mfma_f32_32x32x16_bf16 v[96:111], v[92:95], v[142:145], v[96:111]
	v_add_f32_e32 v92, v139, v130
	ds_read_b64_tr_b16 v[130:131], v251 offset:24576
	v_mov_b32_e32 v93, v92
	s_nop 1
	v_permlane32_swap_b32_e32 v92, v93
	s_waitcnt lgkmcnt(6)
	v_mfma_f32_32x32x16_bf16 v[64:79], v[126:129], v[142:145], v[64:79]
	ds_read_b64_tr_b16 v[124:125], v251 offset:28672
	ds_read_b64_tr_b16 v[126:127], v251 offset:30720
	s_waitcnt lgkmcnt(6)
	v_mfma_f32_32x32x16_bf16 v[0:15], v[80:83], v[116:119], v[0:15]
	v_max3_f32 v94, v96, v97, v98
	v_max3_f32 v94, v94, v99, v100
	v_max3_f32 v94, v94, v101, v102
	ds_read_b64_tr_b16 v[116:117], v251 offset:16896
	ds_read_b64_tr_b16 v[118:119], v251 offset:18944
	v_max3_f32 v94, v94, v103, v104
	v_max3_f32 v94, v94, v105, v106
	v_max3_f32 v94, v94, v107, v108
	v_max3_f32 v94, v94, v109, v110
	v_max_f32_e32 v95, v65, v65
	v_max_f32_e32 v128, v64, v64
	s_waitcnt lgkmcnt(6)
	v_mfma_f32_32x32x16_bf16 v[0:15], v[84:87], v[120:123], v[0:15]
	v_max_f32_e32 v95, v128, v95
	v_max3_f32 v95, v95, v66, v67
	v_max3_f32 v95, v95, v68, v69
	v_max3_f32 v95, v95, v70, v71
	ds_read_b64_tr_b16 v[120:121], v251 offset:20992
	ds_read_b64_tr_b16 v[122:123], v251 offset:23040
	v_max3_f32 v95, v95, v72, v73
	v_max3_f32 v95, v95, v74, v75
	v_max3_f32 v95, v95, v76, v77
	v_max3_f32 v95, v95, v78, v79
	v_max3_f32 v94, v94, v111, v95
	v_mov_b32_e32 v95, v94
	s_waitcnt lgkmcnt(6)
	v_mfma_f32_32x32x16_bf16 v[0:15], v[88:91], v[130:133], v[0:15]
	v_permlane32_swap_b32_e32 v94, v95
	v_max_f32_e32 v95, v95, v95
	v_max_f32_e32 v94, v94, v94
	v_max_f32_e32 v94, v94, v95
	v_sub_f32_e32 v95, v94, v252
	ds_read_b64_tr_b16 v[132:133], v251 offset:25088
	ds_read_b64_tr_b16 v[134:135], v251 offset:27136
	v_cmp_ge_f32_e32 vcc, s33, v95
	s_cmp_eq_u64 vcc, exec
	v_max_f32_e32 v95, v252, v252
	s_cselect_b64 vcc, -1, 0
	v_max_f32_e32 v94, v95, v94
	v_cndmask_b32_e32 v130, v94, v252, vcc
	s_waitcnt lgkmcnt(6)
; __device__ __forceinline__ s16x4 tr_read(LAS unsigned char* p) { return __builtin_bit_cast(s16x4, __builtin_amdgcn_ds_read_tr16_b64_v4i16((LAS v4i16_t*)p)); }
; #define SBAR() __builtin_amdgcn_sched_barrier(0)
; template <int M, int N, class Fn> __device__ __forceinline__ void sfor(Fn&& f) { if constexpr (M < N) { f(std::integral_constant<int, M>{}); sfor<M + 1, N>(f); } }
; template <int OFF> __device__ __forceinline__ s16x4 tr_read(int vb) { return __builtin_amdgcn_ds_read_tr16_b64_v4i16((LAS s16x4*)(unsigned)(vb + OFF)); }
; template <bool PSM, bool PRE> __device__ __forceinline__ void region_pv(f32x16* o, int vb, const bf16x8 (&pa)[4], f32x16& pn0, f32x16& pn1, float& m_reg, float& alpha, s16x4 (&l)[4], s16x4 (&h)[4]) {
;     PsmSt st;
;     if constexpr (!PRE) {
;     l[0] = tr_read<v_rd_off(0, 0, 0)>(vb); h[0] = tr_read<v_rd_off(0, 0, 1)>(vb); l[1] = tr_read<v_rd_off(0, 1, 0)>(vb); h[1] = tr_read<v_rd_off(0, 1, 1)>(vb);
;     l[2] = tr_read<v_rd_off(0, 2, 0)>(vb); h[2] = tr_read<v_rd_off(0, 2, 1)>(vb); l[3] = tr_read<v_rd_off(0, 3, 0)>(vb); h[3] = tr_read<v_rd_off(0, 3, 1)>(vb);
;     SBAR(); }
;     sfor<0, 16>([&](auto n_) { constexpr int n = decltype(n_)::value, b = n >> 2, k = n & 3;
;         o[b] = __builtin_amdgcn_mfma_f32_32x32x16_bf16(pa[k], (bf16x8){l[k][0], l[k][1], l[k][2], l[k][3], h[k][0], h[k][1], h[k][2], h[k][3]}, o[b], 0, 0, 0);
;         if constexpr (b < 3) { l[k] = tr_read<v_rd_off((b + 1) & 3, k, 0)>(vb); h[k] = tr_read<v_rd_off((b + 1) & 3, k, 1)>(vb); }
;         if constexpr (PSM) psm_slice<n>(pn0, pn1, m_reg, alpha, st);
;         __builtin_amdgcn_sched_group_barrier(0x8, 1, 0); __builtin_amdgcn_sched_group_barrier(0x100, 2, 0);
;         SBAR();
;     });
; }
	v_mfma_f32_32x32x16_bf16 v[0:15], v[112:115], v[124:127], v[0:15]
	v_sub_f32_e32 v94, v252, v130
	ds_read_b64_tr_b16 v[124:125], v251 offset:29184
	ds_read_b64_tr_b16 v[126:127], v251 offset:31232
	v_exp_f32_e32 v131, v94
	s_waitcnt lgkmcnt(6)
	v_mfma_f32_32x32x16_bf16 v[48:63], v[80:83], v[116:119], v[48:63]
	v_sub_f32_e32 v94, v96, v130
	v_sub_f32_e32 v95, v97, v130
	ds_read_b64_tr_b16 v[116:117], v251 offset:17408
	ds_read_b64_tr_b16 v[118:119], v251 offset:19456
	v_exp_f32_e32 v94, v94
	v_exp_f32_e32 v95, v95
	s_waitcnt lgkmcnt(6)
	v_mfma_f32_32x32x16_bf16 v[48:63], v[84:87], v[120:123], v[48:63]
	v_sub_f32_e32 v96, v98, v130
	v_sub_f32_e32 v97, v99, v130
	ds_read_b64_tr_b16 v[120:121], v251 offset:21504
	ds_read_b64_tr_b16 v[122:123], v251 offset:23552
	v_exp_f32_e32 v96, v96
	v_exp_f32_e32 v97, v97
	s_waitcnt lgkmcnt(6)
	v_mfma_f32_32x32x16_bf16 v[48:63], v[88:91], v[132:135], v[48:63]
	v_sub_f32_e32 v98, v100, v130
	v_sub_f32_e32 v99, v101, v130
	ds_read_b64_tr_b16 v[132:133], v251 offset:25600
	ds_read_b64_tr_b16 v[134:135], v251 offset:27648
	v_exp_f32_e32 v98, v98
	v_exp_f32_e32 v99, v99
	s_waitcnt lgkmcnt(6)
	v_mfma_f32_32x32x16_bf16 v[48:63], v[112:115], v[124:127], v[48:63]
	v_sub_f32_e32 v100, v102, v130
	v_sub_f32_e32 v101, v103, v130
	ds_read_b64_tr_b16 v[124:125], v251 offset:29696
	ds_read_b64_tr_b16 v[126:127], v251 offset:31744
	v_exp_f32_e32 v100, v100
	v_exp_f32_e32 v101, v101
	s_waitcnt lgkmcnt(6)
	v_mfma_f32_32x32x16_bf16 v[32:47], v[80:83], v[116:119], v[32:47]
	v_sub_f32_e32 v102, v104, v130
	ds_read_b64_tr_b16 v[116:117], v251 offset:17920
	ds_read_b64_tr_b16 v[118:119], v251 offset:19968
	v_exp_f32_e32 v102, v102
	s_waitcnt lgkmcnt(6)
	v_mfma_f32_32x32x16_bf16 v[32:47], v[84:87], v[120:123], v[32:47]
	v_sub_f32_e32 v103, v105, v130
	ds_read_b64_tr_b16 v[120:121], v251 offset:22016
	ds_read_b64_tr_b16 v[122:123], v251 offset:24064
	v_exp_f32_e32 v103, v103
	s_waitcnt lgkmcnt(6)
	v_mfma_f32_32x32x16_bf16 v[32:47], v[88:91], v[132:135], v[32:47]
	v_sub_f32_e32 v104, v106, v130
	ds_read_b64_tr_b16 v[132:133], v251 offset:26112
	ds_read_b64_tr_b16 v[134:135], v251 offset:28160
	v_exp_f32_e32 v104, v104
	s_waitcnt lgkmcnt(6)
	v_mfma_f32_32x32x16_bf16 v[32:47], v[112:115], v[124:127], v[32:47]
	v_sub_f32_e32 v105, v107, v130
	ds_read_b64_tr_b16 v[124:125], v251 offset:30208
	ds_read_b64_tr_b16 v[126:127], v251 offset:32256
	v_exp_f32_e32 v105, v105
	s_waitcnt lgkmcnt(6)
	v_mfma_f32_32x32x16_bf16 v[16:31], v[80:83], v[116:119], v[16:31]
	v_sub_f32_e32 v80, v108, v130
	v_exp_f32_e32 v106, v80
	s_waitcnt lgkmcnt(4)
	v_mfma_f32_32x32x16_bf16 v[16:31], v[84:87], v[120:123], v[16:31]
	v_sub_f32_e32 v80, v109, v130
	v_exp_f32_e32 v107, v80
	s_waitcnt lgkmcnt(2)
	v_mfma_f32_32x32x16_bf16 v[16:31], v[88:91], v[132:135], v[16:31]
	v_sub_f32_e32 v80, v110, v130
	v_exp_f32_e32 v108, v80
	s_waitcnt lgkmcnt(0)
	v_mfma_f32_32x32x16_bf16 v[16:31], v[112:115], v[124:127], v[16:31]
	v_sub_f32_e32 v80, v111, v130
	v_exp_f32_e32 v109, v80
	v_cmp_gt_f32_e32 vcc, 1.0, v131
	s_cbranch_vccz .LBB0_632
	s_and_saveexec_b64 s[48:49], s[40:41]
	ds_write_b32 v215, v131 offset:128
	s_or_b64 exec, exec, s[48:49]
	s_waitcnt lgkmcnt(0)
	ds_read_b128 v[80:83], v250 offset:224
	ds_read_b128 v[84:87], v250 offset:192
	ds_read_b128 v[88:91], v250 offset:160
	ds_read_b128 v[110:113], v250 offset:128
	s_waitcnt lgkmcnt(3)
	v_pk_mul_f32 v[14:15], v[14:15], v[82:83]
	s_waitcnt lgkmcnt(2)
	v_pk_mul_f32 v[10:11], v[10:11], v[86:87]
	s_waitcnt lgkmcnt(1)
	v_pk_mul_f32 v[6:7], v[6:7], v[90:91]
	s_waitcnt lgkmcnt(0)
	v_pk_mul_f32 v[2:3], v[2:3], v[112:113]
	v_pk_mul_f32 v[12:13], v[12:13], v[80:81]
	v_pk_mul_f32 v[8:9], v[8:9], v[84:85]
	v_pk_mul_f32 v[4:5], v[4:5], v[88:89]
	v_pk_mul_f32 v[0:1], v[0:1], v[110:111]
	v_pk_mul_f32 v[62:63], v[62:63], v[82:83]
	v_pk_mul_f32 v[58:59], v[58:59], v[86:87]
	v_pk_mul_f32 v[54:55], v[54:55], v[90:91]
	v_pk_mul_f32 v[50:51], v[50:51], v[112:113]
	v_pk_mul_f32 v[60:61], v[60:61], v[80:81]
	v_pk_mul_f32 v[56:57], v[56:57], v[84:85]
	v_pk_mul_f32 v[52:53], v[52:53], v[88:89]
	v_pk_mul_f32 v[48:49], v[48:49], v[110:111]
	v_pk_mul_f32 v[46:47], v[46:47], v[82:83]
	v_pk_mul_f32 v[42:43], v[42:43], v[86:87]
	v_pk_mul_f32 v[38:39], v[38:39], v[90:91]
	v_pk_mul_f32 v[34:35], v[34:35], v[112:113]
	v_pk_mul_f32 v[44:45], v[44:45], v[80:81]
	v_pk_mul_f32 v[40:41], v[40:41], v[84:85]
	v_pk_mul_f32 v[36:37], v[36:37], v[88:89]
	v_pk_mul_f32 v[32:33], v[32:33], v[110:111]
	v_pk_mul_f32 v[30:31], v[30:31], v[82:83]
	v_pk_mul_f32 v[26:27], v[26:27], v[86:87]
	v_pk_mul_f32 v[22:23], v[22:23], v[90:91]
	v_pk_mul_f32 v[18:19], v[18:19], v[112:113]
	v_pk_mul_f32 v[28:29], v[28:29], v[80:81]
	v_pk_mul_f32 v[24:25], v[24:25], v[84:85]
	v_pk_mul_f32 v[20:21], v[20:21], v[88:89]
	v_pk_mul_f32 v[16:17], v[16:17], v[110:111]
	.p2align 6

; #define GAS __attribute__((address_space(1)))
; #define LAS __attribute__((address_space(3)))
; __device__ __forceinline__ unsigned argw(const Frame& F, int w) { return ((const volatile LAS unsigned*)(F.lds + ARGS_OFF + F.zero))[w]; }
; __device__ __forceinline__ void pmat_phase(const Frame& F, const bf16_t* Q, const bf16_t* K, bf16_t* PB, int half) {
;     const int nseq = half ? NS : NP, nchunk = half ? LP_S / 128 : LP_P / 128;
;     const int nunits = nseq * nchunk * RH;
;     const int tid = F.tid, lane = tid & 63, wv = tid >> 6, l15 = lane & 15, quad = lane >> 4;
;     LAS unsigned char* const lg = F.lds;
;     LAS unsigned char* const bQown = lg + (16 * wv + l15) * PS + 16 * quad;
;     LAS unsigned char* const bK    = lg + 128 * PS + l15 * PS + 16 * quad;
;     const int srow = tid >> 5, scc = tid & 31;
;     for (int u = F.vcu; u < nunits; u += F.G) {
;         const int head = u & 7, sc = u >> 3;
;         const float lgf = __uint_as_float(__builtin_amdgcn_readfirstlane(argw(F, AW_LG2 + head))), lgb = __uint_as_float(__builtin_amdgcn_readfirstlane(argw(F, AW_LG2 + 8 + head)));
;         const size_t u0 = (size_t)sc * 128 * 2048 + head * 256; const unsigned lq = (unsigned)(srow * 2048 + scc * 8);
; #pragma unroll
;         for (int ii = 0; ii < 8; ++ii) { const u32x4 qv = *(const GAS u32x4*)(Q + u0 + (size_t)ii * 16 * 2048 + lq), kv = *(const GAS u32x4*)(K + u0 + (size_t)ii * 16 * 2048 + lq);
;             *(LAS u32x4*)(lg + (srow + 16 * ii) * PS + scc * 16) = qv; *(LAS u32x4*)(lg + 128 * PS + (srow + 16 * ii) * PS + scc * 16) = kv; }
;         __syncthreads();
;         bf16x8 Qf[8];
; #pragma unroll
;         for (int ks = 0; ks < 8; ++ks) Qf[ks] = *(const LAS bf16x8*)(bQown + 64 * ks);
;         bf16_t* pout = PB + (size_t)u * 16384; const unsigned lpo = (unsigned)((16 * wv + l15) * 128 + 4 * quad); const int i_abs = 16 * wv + l15;
; #pragma unroll
;         for (int jt = 0; jt < 8; ++jt) { f32x4 st = {0.f, 0.f, 0.f, 0.f};
; #pragma unroll
;             for (int ks = 0; ks < 8; ++ks) { const bf16x8 Kf = *(const LAS bf16x8*)(bK + 16 * jt * PS + 64 * ks); st = __builtin_amdgcn_mfma_f32_16x16x32_bf16(Kf, Qf[ks], st, 0, 0, 0); }
; #pragma unroll
;             for (int r = 0; r < 4; ++r) { const int jj = 16 * jt + 4 * quad + r;
;                 st[r] *= __builtin_amdgcn_exp2f(jj <= i_abs ? lgf * (float)(-jj - 1) : lgb * (float)(jj - 128)); }
.LBB0_912:
	v_readlane_b32 s0, v254, 3
	v_readlane_b32 s1, v254, 4
	s_cmp_ge_i32 s18, s0
	s_cselect_b64 s[0:1], -1, 0
	v_writelane_b32 v255, s0, 61
	s_nop 1
	v_writelane_b32 v255, s1, 62
	s_and_b64 s[0:1], s[0:1], s[22:23]
	s_andn2_b64 vcc, exec, s[0:1]
	s_cbranch_vccnz .LBB0_917
	s_mov_b32 s0, -1
	v_readlane_b32 s28, v255, 58
	v_mbcnt_lo_u32_b32 v0, s0, 0
	v_mbcnt_hi_u32_b32 v0, s0, v0
	v_readlane_b32 s0, v254, 5
	v_readlane_b32 s29, v255, 59
	s_and_b64 s[36:37], s[28:29], exec
	v_add_u32_e32 v1, s0, v0
	v_readlane_b32 s0, v254, 2
	s_mov_b32 s22, s0
	v_mov_b32_e32 v0, v193
	s_movk_i32 s13, 0x820
	v_add_u32_e32 v2, 0, v0
	v_add_u32_e32 v3, 0x23ba8, v2
	ds_read_b32 v3, v3
	v_add_u32_e32 v4, 0x23bac, v2
	v_add_u32_e32 v5, 0x23ba0, v2
	v_add_u32_e32 v2, 0x23ba4, v2
	ds_read_b32 v4, v4
	ds_read_b32 v6, v5
	ds_read_b32 v7, v2
	s_waitcnt lgkmcnt(0)
	v_readfirstlane_b32 s0, v3
	ds_read_b32 v3, v5
	ds_read_b32 v2, v2
	s_cselect_b32 s18, s13, 0x840
	v_readfirstlane_b32 s1, v4
	v_readfirstlane_b32 s34, v6
	v_readfirstlane_b32 s35, v7
	s_waitcnt lgkmcnt(0)
	v_readfirstlane_b32 s12, v3
	s_cmp_ge_i32 s22, s18
	v_readfirstlane_b32 s13, v2
	s_cbranch_scc1 .LBB0_917
	v_ashrrev_i32_e32 v8, 2, v1
	v_bfi_b32 v9, -16, v8, v1
	s_movk_i32 s15, 0x210
	v_and_b32_e32 v6, 15, v1
	v_bfe_u32 v7, v1, 4, 2
	v_mul_lo_u32 v2, v9, s15
	v_add_u32_e32 v10, 0, v2
	v_lshlrev_b32_e32 v11, 4, v7
	v_mul_u32_u24_e32 v2, 0x210, v6
	v_readlane_b32 s23, v255, 23
	v_ashrrev_i32_e32 v12, 5, v1
	v_and_b32_e32 v1, 31, v1
	v_add3_u32 v38, s23, v2, v11
	v_lshlrev_b32_e32 v2, 3, v1
	v_lshl_or_b32 v192, v12, 11, v2
	v_lshlrev_b64 v[2:3], 1, v[192:193]
	v_lshl_add_u64 v[4:5], s[34:35], 0, v[2:3]
	v_lshl_add_u64 v[2:3], s[0:1], 0, v[2:3]
	s_mov_b64 s[0:1], 0x4a900000
	v_lshlrev_b32_e32 v1, 4, v1
	s_mov_b64 s[34:35], 0x10800000
	v_lshl_add_u64 v[34:35], v[2:3], 0, s[0:1]
	v_add_u32_e32 v2, 0, v1
	v_add_u32_e32 v3, s23, v1
	v_lshlrev_b32_e32 v1, 2, v7
	v_lshl_add_u64 v[32:33], v[4:5], 0, s[34:35]
	v_not_b32_e32 v5, v1
	v_cvt_f32_i32_e32 v39, v5
	v_or_b32_e32 v5, 0xffffff80, v1
	v_cvt_f32_i32_e32 v40, v5
	v_or_b32_e32 v5, 0xffffff81, v1
	v_cvt_f32_i32_e32 v41, v5
	v_xor_b32_e32 v5, -2, v1
	v_cvt_f32_i32_e32 v42, v5
	v_or_b32_e32 v5, 2, v1
	v_cmp_gt_i32_e64 s[36:37], v5, v9
	v_xor_b32_e32 v5, -3, v1
	v_cvt_f32_i32_e32 v43, v5
	v_or_b32_e32 v5, 0xffffff82, v1
	v_cvt_f32_i32_e32 v44, v5
	v_or_b32_e32 v5, 3, v1
	v_cmp_gt_i32_e64 s[38:39], v5, v9
	v_xor_b32_e32 v5, -4, v1
	v_cvt_f32_i32_e32 v45, v5
	v_or_b32_e32 v5, 0xffffff83, v1
	v_cvt_f32_i32_e32 v46, v5
	v_or_b32_e32 v5, 16, v1
	v_cmp_gt_i32_e64 s[40:41], v5, v9
	v_xor_b32_e32 v5, 0xffffffef, v1
	v_cvt_f32_i32_e32 v47, v5
	v_or_b32_e32 v5, 0xffffff90, v1
	v_cvt_f32_i32_e32 v48, v5
	v_or_b32_e32 v5, 17, v1
	v_cmp_gt_i32_e64 s[42:43], v5, v9
	v_xor_b32_e32 v5, 0xffffffee, v1
	v_cvt_f32_i32_e32 v49, v5
	v_or_b32_e32 v5, 0xffffff91, v1
	v_cvt_f32_i32_e32 v50, v5
	v_or_b32_e32 v5, 18, v1
	v_cmp_gt_i32_e64 s[44:45], v5, v9
	v_xor_b32_e32 v5, 0xffffffed, v1
	v_cvt_f32_i32_e32 v51, v5
	v_or_b32_e32 v5, 0xffffff92, v1
	v_cvt_f32_i32_e32 v52, v5
	v_or_b32_e32 v5, 19, v1
	v_cmp_gt_i32_e64 s[46:47], v5, v9
	v_xor_b32_e32 v5, 0xffffffec, v1
	v_cvt_f32_i32_e32 v53, v5
	v_or_b32_e32 v5, 0xffffff93, v1
	v_cvt_f32_i32_e32 v54, v5
	v_or_b32_e32 v5, 32, v1
	v_cmp_gt_i32_e64 s[48:49], v5, v9
	v_xor_b32_e32 v5, 0xffffffdf, v1
	v_cvt_f32_i32_e32 v55, v5
	v_or_b32_e32 v5, 0xffffffa0, v1
	v_cvt_f32_i32_e32 v56, v5
	v_or_b32_e32 v5, 33, v1
	v_cmp_gt_i32_e64 s[50:51], v5, v9
	v_xor_b32_e32 v5, 0xffffffde, v1
	v_cvt_f32_i32_e32 v57, v5
	v_or_b32_e32 v5, 0xffffffa1, v1
	v_cvt_f32_i32_e32 v58, v5
	v_or_b32_e32 v5, 34, v1
	v_cmp_gt_i32_e64 s[52:53], v5, v9
	v_xor_b32_e32 v5, 0xffffffdd, v1
	v_cvt_f32_i32_e32 v59, v5
	v_or_b32_e32 v5, 0xffffffa2, v1
	v_cvt_f32_i32_e32 v60, v5
	v_or_b32_e32 v5, 35, v1
	v_cmp_gt_i32_e64 s[54:55], v5, v9
	v_xor_b32_e32 v5, 0xffffffdc, v1
	v_cvt_f32_i32_e32 v61, v5
	v_or_b32_e32 v5, 0xffffffa3, v1
	v_cvt_f32_i32_e32 v62, v5
	v_or_b32_e32 v5, 48, v1
	v_cmp_gt_i32_e64 s[56:57], v5, v9
	v_xor_b32_e32 v5, 0xffffffcf, v1
	v_cvt_f32_i32_e32 v63, v5
	v_or_b32_e32 v5, 0xffffffb0, v1
	s_waitcnt vmcnt(0)
; #define GAS __attribute__((address_space(1)))
; #define LAS __attribute__((address_space(3)))
; __device__ __forceinline__ unsigned argw(const Frame& F, int w) { return ((const volatile LAS unsigned*)(F.lds + ARGS_OFF + F.zero))[w]; }
; __device__ __forceinline__ void pmat_phase(const Frame& F, const bf16_t* Q, const bf16_t* K, bf16_t* PB, int half) {
;     ...
;     for (int u = F.vcu; u < nunits; u += F.G) {
;         const int head = u & 7, sc = u >> 3;
;         const float lgf = __uint_as_float(__builtin_amdgcn_readfirstlane(argw(F, AW_LG2 + head))), lgb = __uint_as_float(__builtin_amdgcn_readfirstlane(argw(F, AW_LG2 + 8 + head)));
;         const size_t u0 = (size_t)sc * 128 * 2048 + head * 256; const unsigned lq = (unsigned)(srow * 2048 + scc * 8);
; #pragma unroll
;         for (int ii = 0; ii < 8; ++ii) { const u32x4 qv = *(const GAS u32x4*)(Q + u0 + (size_t)ii * 16 * 2048 + lq), kv = *(const GAS u32x4*)(K + u0 + (size_t)ii * 16 * 2048 + lq);
;             *(LAS u32x4*)(lg + (srow + 16 * ii) * PS + scc * 16) = qv; *(LAS u32x4*)(lg + 128 * PS + (srow + 16 * ii) * PS + scc * 16) = kv; }
	v_cvt_f32_i32_e32 v64, v5
	v_or_b32_e32 v5, 49, v1
	v_cmp_gt_i32_e64 s[58:59], v5, v9
	v_xor_b32_e32 v5, 0xffffffce, v1
	v_cvt_f32_i32_e32 v65, v5
	v_or_b32_e32 v5, 0xffffffb1, v1
	v_cvt_f32_i32_e32 v66, v5
	v_or_b32_e32 v5, 50, v1
	v_cmp_gt_i32_e64 s[60:61], v5, v9
	v_xor_b32_e32 v5, 0xffffffcd, v1
	v_cvt_f32_i32_e32 v67, v5
	v_or_b32_e32 v5, 0xffffffb2, v1
	v_cvt_f32_i32_e32 v68, v5
	v_or_b32_e32 v5, 51, v1
	v_cmp_gt_i32_e64 s[62:63], v5, v9
	v_xor_b32_e32 v5, 0xffffffcc, v1
	v_cvt_f32_i32_e32 v69, v5
	v_or_b32_e32 v5, 0xffffffb3, v1
	v_cvt_f32_i32_e32 v70, v5
	v_or_b32_e32 v5, 64, v1
	v_cmp_gt_i32_e64 s[64:65], v5, v9
	v_xor_b32_e32 v5, 0xffffffbf, v1
	v_cvt_f32_i32_e32 v71, v5
	v_or_b32_e32 v5, 0xffffffc0, v1
	v_cvt_f32_i32_e32 v72, v5
	v_or_b32_e32 v5, 0x41, v1
	v_cmp_gt_i32_e64 s[66:67], v5, v9
	v_xor_b32_e32 v5, 0xffffffbe, v1
	v_cvt_f32_i32_e32 v73, v5
	v_or_b32_e32 v5, 0xffffffc1, v1
	v_cvt_f32_i32_e32 v74, v5
	v_or_b32_e32 v5, 0x42, v1
	v_cmp_gt_i32_e64 s[68:69], v5, v9
	v_xor_b32_e32 v5, 0xffffffbd, v1
	v_cvt_f32_i32_e32 v75, v5
	v_or_b32_e32 v5, 0xffffffc2, v1
	v_cvt_f32_i32_e32 v76, v5
	v_or_b32_e32 v5, 0x43, v1
	v_cmp_gt_i32_e64 s[70:71], v5, v9
	v_xor_b32_e32 v5, 0xffffffbc, v1
	v_cvt_f32_i32_e32 v77, v5
	v_or_b32_e32 v5, 0xffffffc3, v1
	v_cvt_f32_i32_e32 v78, v5
	v_or_b32_e32 v5, 0x50, v1
	v_cmp_gt_i32_e64 s[72:73], v5, v9
	v_xor_b32_e32 v5, 0xffffffaf, v1
	v_cvt_f32_i32_e32 v79, v5
	v_or_b32_e32 v5, 0xffffffd0, v1
	v_cvt_f32_i32_e32 v80, v5
	v_or_b32_e32 v5, 0x51, v1
	v_cmp_gt_i32_e64 s[74:75], v5, v9
	v_xor_b32_e32 v5, 0xffffffae, v1
	v_cvt_f32_i32_e32 v81, v5
	v_or_b32_e32 v5, 0xffffffd1, v1
	v_cvt_f32_i32_e32 v82, v5
	v_or_b32_e32 v5, 0x52, v1
	v_cmp_gt_i32_e64 s[76:77], v5, v9
	v_xor_b32_e32 v5, 0xffffffad, v1
	v_cvt_f32_i32_e32 v83, v5
	v_or_b32_e32 v5, 0xffffffd2, v1
	v_cvt_f32_i32_e32 v84, v5
	v_or_b32_e32 v5, 0x53, v1
	v_cmp_gt_i32_e64 s[78:79], v5, v9
	v_xor_b32_e32 v5, 0xffffffac, v1
	v_cvt_f32_i32_e32 v85, v5
	v_or_b32_e32 v5, 0xffffffd3, v1
	v_cvt_f32_i32_e32 v86, v5
	v_or_b32_e32 v5, 0x60, v1
	v_cmp_gt_i32_e64 s[80:81], v5, v9
	v_xor_b32_e32 v5, 0xffffff9f, v1
	v_cvt_f32_i32_e32 v87, v5
	v_or_b32_e32 v5, 0xffffffe0, v1
	v_cvt_f32_i32_e32 v88, v5
	v_or_b32_e32 v5, 0x61, v1
	v_cmp_gt_i32_e64 s[82:83], v5, v9
	v_xor_b32_e32 v5, 0xffffff9e, v1
	v_cvt_f32_i32_e32 v89, v5
	v_or_b32_e32 v5, 0xffffffe1, v1
	v_cvt_f32_i32_e32 v90, v5
	v_or_b32_e32 v5, 0x62, v1
	v_cmp_gt_i32_e64 s[84:85], v5, v9
	v_xor_b32_e32 v5, 0xffffff9d, v1
	v_cvt_f32_i32_e32 v91, v5
	v_or_b32_e32 v5, 0xffffffe2, v1
	v_cvt_f32_i32_e32 v92, v5
	v_or_b32_e32 v5, 0x63, v1
	v_cmp_gt_i32_e64 s[86:87], v5, v9
	v_xor_b32_e32 v5, 0xffffff9c, v1
	v_cvt_f32_i32_e32 v93, v5
	v_or_b32_e32 v5, 0xffffffe3, v1
	v_cvt_f32_i32_e32 v94, v5
	v_or_b32_e32 v5, 0x70, v1
	v_cmp_gt_i32_e64 s[88:89], v5, v9
	v_xor_b32_e32 v5, 0xffffff8f, v1
	v_cvt_f32_i32_e32 v95, v5
	v_or_b32_e32 v5, -16, v1
	v_cvt_f32_i32_e32 v96, v5
	v_or_b32_e32 v5, 0x71, v1
	v_cmp_gt_i32_e64 s[90:91], v5, v9
	v_xor_b32_e32 v5, 0xffffff8e, v1
	v_cvt_f32_i32_e32 v97, v5
	v_or_b32_e32 v5, -15, v1
	v_cvt_f32_i32_e32 v98, v5
	v_or_b32_e32 v5, 0x72, v1
	v_cmp_gt_i32_e64 s[92:93], v5, v9
	v_xor_b32_e32 v5, 0xffffff8d, v1
	v_cvt_f32_i32_e32 v99, v5
	v_or_b32_e32 v5, -14, v1
	v_cvt_f32_i32_e32 v100, v5
	v_or_b32_e32 v5, 0x73, v1
	s_add_i32 s23, 0, 0x23b00
	v_cmp_gt_i32_e64 s[94:95], v5, v9
	v_xor_b32_e32 v5, 0xffffff8c, v1
	v_add_u32_e32 v103, s23, v0
	s_ashr_i32 s23, s22, 31
	v_cvt_f32_i32_e32 v101, v5
	v_or_b32_e32 v5, -13, v1
	s_lshl_b64 vcc, s[22:23], 15
	v_lshlrev_b32_e32 v0, 7, v8
	v_cvt_f32_i32_e32 v102, v5
	v_and_b32_e32 v0, 0xfffff800, v0
	v_lshlrev_b32_e32 v5, 7, v6
	s_add_u32 s12, s12, vcc_lo
	v_or3_b32 v192, v0, v5, v1
	s_addc_u32 s13, s13, vcc_hi
	v_mul_lo_u32 v4, v12, s15
	v_cmp_gt_i32_e64 s[0:1], v1, v9
	v_cmp_lt_i32_e64 s[34:35], v1, v9
	v_lshl_add_u64 v[0:1], v[192:193], 1, s[12:13]
	s_mov_b64 s[12:13], 0x18c00000
	v_readlane_b32 s30, v255, 29
	v_lshl_add_u64 v[36:37], v[0:1], 0, s[12:13]
	v_add_u32_e32 v104, v2, v4
	v_add_u32_e32 v105, v3, v4
	v_add_u32_e32 v106, v10, v11
	s_mov_b32 s15, 0x10000
	s_mov_b32 s33, 0x20000
	s_mov_b32 s3, 0x30000
	s_mov_b32 s10, 0x50000
	s_mov_b32 s28, 0x60000
	s_mov_b32 s29, 0x70000
	v_readlane_b32 s31, v255, 30
	s_and_b32 s13, s22, 7
	s_ashr_i32 vcc_lo, s22, 3
	s_ashr_i32 vcc_hi, vcc_lo, 31
	s_lshl_b64 vcc, vcc, 19
	s_lshl_b32 s13, s13, 9
	s_or_b32 vcc_lo, vcc_lo, s13
	v_lshl_add_u64 v[194:195], v[32:33], 0, vcc
	v_lshl_add_u64 v[196:197], v[34:35], 0, vcc
	global_load_dwordx4 v[128:131], v[194:195], off
	global_load_dwordx4 v[132:135], v[196:197], off
	v_add_co_u32_e32 v198, vcc, s15, v194
	s_nop 1
	v_addc_co_u32_e32 v199, vcc, 0, v195, vcc
	global_load_dwordx4 v[136:139], v[198:199], off
	v_add_co_u32_e32 v200, vcc, s15, v196
	s_nop 1
	v_addc_co_u32_e32 v201, vcc, 0, v197, vcc
	global_load_dwordx4 v[140:143], v[200:201], off
	v_add_co_u32_e32 v198, vcc, s33, v194
	s_nop 1
	v_addc_co_u32_e32 v199, vcc, 0, v195, vcc
	global_load_dwordx4 v[144:147], v[198:199], off
	v_add_co_u32_e32 v200, vcc, s33, v196
	s_nop 1
	v_addc_co_u32_e32 v201, vcc, 0, v197, vcc
	global_load_dwordx4 v[148:151], v[200:201], off
	v_add_co_u32_e32 v198, vcc, s3, v194
	s_nop 1
	v_addc_co_u32_e32 v199, vcc, 0, v195, vcc
	global_load_dwordx4 v[152:155], v[198:199], off
	v_add_co_u32_e32 v200, vcc, s3, v196
	s_nop 1
	v_addc_co_u32_e32 v201, vcc, 0, v197, vcc
	global_load_dwordx4 v[156:159], v[200:201], off
	v_add_co_u32_e32 v198, vcc, s96, v194
	s_nop 1
	v_addc_co_u32_e32 v199, vcc, 0, v195, vcc
	global_load_dwordx4 v[160:163], v[198:199], off
	v_add_co_u32_e32 v200, vcc, s96, v196
	s_nop 1
	v_addc_co_u32_e32 v201, vcc, 0, v197, vcc
	global_load_dwordx4 v[164:167], v[200:201], off
	v_add_co_u32_e32 v198, vcc, s10, v194
	s_nop 1
	v_addc_co_u32_e32 v199, vcc, 0, v195, vcc
	global_load_dwordx4 v[168:171], v[198:199], off
	v_add_co_u32_e32 v200, vcc, s10, v196
	s_nop 1
	v_addc_co_u32_e32 v201, vcc, 0, v197, vcc
	global_load_dwordx4 v[172:175], v[200:201], off
	v_add_co_u32_e32 v198, vcc, s28, v194
	s_nop 1
	v_addc_co_u32_e32 v199, vcc, 0, v195, vcc
	global_load_dwordx4 v[176:179], v[198:199], off
	v_add_co_u32_e32 v200, vcc, s28, v196
	s_nop 1
	v_addc_co_u32_e32 v201, vcc, 0, v197, vcc
	global_load_dwordx4 v[180:183], v[200:201], off
	v_add_co_u32_e32 v198, vcc, s29, v194
	s_nop 1
	v_addc_co_u32_e32 v199, vcc, 0, v195, vcc
	global_load_dwordx4 v[184:187], v[198:199], off
	v_add_co_u32_e32 v200, vcc, s29, v196
	s_nop 1
	v_addc_co_u32_e32 v201, vcc, 0, v197, vcc
	global_load_dwordx4 v[188:191], v[200:201], off
	s_waitcnt vmcnt(0)
	.p2align 6
